# FFN-in K-loop LDS-DMA loads in SGPR-base + 32-bit VGPR-offset form (16 v_lshl_add_u64 per iteration and wave removed)
# speedup vs baseline: 1.0021x; 1.0021x over previous
.LBB0_477:
	s_ashr_i32 s17, s16, 31
	s_lshl_b64 s[18:19], s[16:17], 19
	s_add_u32 s18, s0, s18
	s_addc_u32 s19, s1, s19
	s_and_b64 s[24:25], s[38:39], exec
	s_cselect_b32 s4, s19, s41
	s_cselect_b32 s9, s18, s40
	s_ashr_i32 s85, s84, 31
	s_lshl_b64 s[24:25], s[84:85], 19
	s_add_u32 s82, s80, s24
	s_addc_u32 s83, s81, s25
	s_and_b64 s[24:25], s[38:39], exec
	s_cselect_b32 s17, s83, s13
	s_cselect_b32 s24, s82, s12
	s_add_u32 s40, s40, 0x40080
	s_addc_u32 s41, s41, 0
	s_add_u32 s25, s12, 0x100
	s_addc_u32 s50, s13, 0
	s_mov_b32 s51, -2
	s_add_u32 s12, s40, 0xfffc0080
	s_addc_u32 s13, s41, -1
	s_add_i32 s85, 0, 0x10000
	s_cmp_eq_u32 s51, 12
	s_cselect_b32 s43, s4, s13
	s_cselect_b32 s42, s9, s12
	v_add_u32_e32 v158, s85, v196
	s_cselect_b32 s13, s17, s50
	s_cselect_b32 s12, s24, s25
	s_add_i32 s27, 0, 0x14000
	ds_read_b128 v[150:153], v158
	ds_read_b128 v[154:157], v158 offset:1024
	ds_read_b128 v[170:173], v158 offset:2048
	ds_read_b128 v[174:177], v158 offset:3072
	v_add_u32_e32 v158, s27, v196
	ds_read_b128 v[178:181], v158
	ds_read_b128 v[182:185], v158 offset:1024
	ds_read_b128 v[186:189], v158 offset:2048
	ds_read_b128 v[200:203], v158 offset:3072
	s_add_i32 m0, s15, 0xc000
	ds_read_b128 v[204:207], v199
	ds_read_b128 v[208:211], v199 offset:1024
	ds_read_b128 v[212:215], v199 offset:2048
	ds_read_b128 v[234:237], v199 offset:3072
	ds_read_b128 v[238:241], v199 offset:4096
	ds_read_b128 v[242:245], v199 offset:5120
	ds_read_b128 v[246:249], v199 offset:6144
	ds_read_b128 v[222:225], v199 offset:7168
	global_load_lds_dwordx4 v146, s[40:41]
	s_add_i32 m0, s15, 0xe000
	s_nop 0
	global_load_lds_dwordx4 v148, s[40:41]
	s_waitcnt vmcnt(8)
	s_waitcnt lgkmcnt(0)
	s_barrier
	s_setprio 1
	s_waitcnt lgkmcnt(0)
	v_mfma_f32_16x16x32_bf16 v[124:127], v[150:153], v[204:207], 0
	v_mfma_f32_16x16x32_bf16 v[120:123], v[170:173], v[204:207], 0
	v_mfma_f32_16x16x32_bf16 v[108:111], v[150:153], v[212:215], 0
	v_mfma_f32_16x16x32_bf16 v[104:107], v[170:173], v[212:215], 0
	v_mfma_f32_16x16x32_bf16 v[92:95], v[150:153], v[238:241], 0
	v_mfma_f32_16x16x32_bf16 v[88:91], v[170:173], v[238:241], 0
	v_mfma_f32_16x16x32_bf16 v[76:79], v[150:153], v[246:249], 0
	v_mfma_f32_16x16x32_bf16 v[72:75], v[170:173], v[246:249], 0
	v_mfma_f32_16x16x32_bf16 v[124:127], v[154:157], v[208:211], v[124:127]
	v_mfma_f32_16x16x32_bf16 v[120:123], v[174:177], v[208:211], v[120:123]
	v_mfma_f32_16x16x32_bf16 v[108:111], v[154:157], v[234:237], v[108:111]
	v_mfma_f32_16x16x32_bf16 v[104:107], v[174:177], v[234:237], v[104:107]
	v_mfma_f32_16x16x32_bf16 v[92:95], v[154:157], v[242:245], v[92:95]
	v_mfma_f32_16x16x32_bf16 v[88:91], v[174:177], v[242:245], v[88:91]
	v_mfma_f32_16x16x32_bf16 v[76:79], v[154:157], v[222:225], v[76:79]
	v_mfma_f32_16x16x32_bf16 v[72:75], v[174:177], v[222:225], v[72:75]
	v_mfma_f32_16x16x32_bf16 v[116:119], v[178:181], v[204:207], 0
	v_mfma_f32_16x16x32_bf16 v[112:115], v[186:189], v[204:207], 0
	v_mfma_f32_16x16x32_bf16 v[100:103], v[178:181], v[212:215], 0
	v_mfma_f32_16x16x32_bf16 v[96:99], v[186:189], v[212:215], 0
	v_mfma_f32_16x16x32_bf16 v[84:87], v[178:181], v[238:241], 0
	v_mfma_f32_16x16x32_bf16 v[80:83], v[186:189], v[238:241], 0
	v_mfma_f32_16x16x32_bf16 v[68:71], v[178:181], v[246:249], 0
	v_mfma_f32_16x16x32_bf16 v[64:67], v[186:189], v[246:249], 0
	v_mfma_f32_16x16x32_bf16 v[116:119], v[182:185], v[208:211], v[116:119]
	v_mfma_f32_16x16x32_bf16 v[112:115], v[200:203], v[208:211], v[112:115]
	v_mfma_f32_16x16x32_bf16 v[100:103], v[182:185], v[234:237], v[100:103]
	v_mfma_f32_16x16x32_bf16 v[96:99], v[200:203], v[234:237], v[96:99]
	v_mfma_f32_16x16x32_bf16 v[84:87], v[182:185], v[242:245], v[84:87]
	v_mfma_f32_16x16x32_bf16 v[80:83], v[200:203], v[242:245], v[80:83]
	v_mfma_f32_16x16x32_bf16 v[68:71], v[182:185], v[222:225], v[68:71]
	v_mfma_f32_16x16x32_bf16 v[64:67], v[200:203], v[222:225], v[64:67]
	s_setprio 0
	s_barrier
	s_add_i32 s85, s85, s86
	s_mov_b32 m0, s85
	ds_read_b128 v[204:207], v199 offset:16384
	ds_read_b128 v[208:211], v199 offset:17408
	ds_read_b128 v[212:215], v199 offset:18432
	ds_read_b128 v[222:225], v199 offset:19456
	ds_read_b128 v[234:237], v199 offset:20480
	ds_read_b128 v[238:241], v199 offset:21504
	ds_read_b128 v[242:245], v199 offset:22528
	ds_read_b128 v[246:249], v199 offset:23552
	global_load_lds_dwordx4 v130, s[12:13]
	s_add_i32 m0, s85, 0x2000
	s_add_u32 s98, s12, 0x40000
	s_addc_u32 s99, s13, 0
	s_add_i32 s27, s27, s86
	global_load_lds_dwordx4 v134, s[12:13]
	s_mov_b32 m0, s27
	s_nop 0
	global_load_lds_dwordx4 v130, s[98:99]
	s_add_i32 m0, s27, 0x2000
	s_nop 0
	global_load_lds_dwordx4 v134, s[98:99]
	s_mov_b32 m0, s15
	s_nop 0
	global_load_lds_dwordx4 v128, s[42:43]
	s_mov_b32 m0, s87
	s_nop 0
	global_load_lds_dwordx4 v132, s[42:43]
	s_waitcnt vmcnt(8)
	s_waitcnt lgkmcnt(0)
	s_barrier
	s_setprio 1
	s_waitcnt lgkmcnt(0)
	v_mfma_f32_16x16x32_bf16 v[60:63], v[150:153], v[204:207], 0
	v_mfma_f32_16x16x32_bf16 v[56:59], v[170:173], v[204:207], 0
	v_mfma_f32_16x16x32_bf16 v[44:47], v[150:153], v[212:215], 0
	v_mfma_f32_16x16x32_bf16 v[40:43], v[170:173], v[212:215], 0
	v_mfma_f32_16x16x32_bf16 v[28:31], v[150:153], v[234:237], 0
	v_mfma_f32_16x16x32_bf16 v[24:27], v[170:173], v[234:237], 0
	v_mfma_f32_16x16x32_bf16 v[12:15], v[150:153], v[242:245], 0
	v_mfma_f32_16x16x32_bf16 v[8:11], v[170:173], v[242:245], 0
	v_mfma_f32_16x16x32_bf16 v[60:63], v[154:157], v[208:211], v[60:63]
	v_mfma_f32_16x16x32_bf16 v[56:59], v[174:177], v[208:211], v[56:59]
	v_mfma_f32_16x16x32_bf16 v[44:47], v[154:157], v[222:225], v[44:47]
	v_mfma_f32_16x16x32_bf16 v[40:43], v[174:177], v[222:225], v[40:43]
	v_mfma_f32_16x16x32_bf16 v[28:31], v[154:157], v[238:241], v[28:31]
	v_mfma_f32_16x16x32_bf16 v[24:27], v[174:177], v[238:241], v[24:27]
	v_mfma_f32_16x16x32_bf16 v[12:15], v[154:157], v[246:249], v[12:15]
	v_mfma_f32_16x16x32_bf16 v[8:11], v[174:177], v[246:249], v[8:11]
	v_mfma_f32_16x16x32_bf16 v[52:55], v[178:181], v[204:207], 0
	v_mfma_f32_16x16x32_bf16 v[48:51], v[186:189], v[204:207], 0
	v_mfma_f32_16x16x32_bf16 v[36:39], v[178:181], v[212:215], 0
	v_mfma_f32_16x16x32_bf16 v[32:35], v[186:189], v[212:215], 0
	v_mfma_f32_16x16x32_bf16 v[20:23], v[178:181], v[234:237], 0
	v_mfma_f32_16x16x32_bf16 v[16:19], v[186:189], v[234:237], 0
	v_mfma_f32_16x16x32_bf16 v[4:7], v[178:181], v[242:245], 0
	v_mfma_f32_16x16x32_bf16 v[0:3], v[186:189], v[242:245], 0
	v_mfma_f32_16x16x32_bf16 v[52:55], v[182:185], v[208:211], v[52:55]
	v_mfma_f32_16x16x32_bf16 v[48:51], v[200:203], v[208:211], v[48:51]
	v_mfma_f32_16x16x32_bf16 v[36:39], v[182:185], v[222:225], v[36:39]
	v_mfma_f32_16x16x32_bf16 v[32:35], v[200:203], v[222:225], v[32:35]
	v_mfma_f32_16x16x32_bf16 v[20:23], v[182:185], v[238:241], v[20:23]
	v_mfma_f32_16x16x32_bf16 v[16:19], v[200:203], v[238:241], v[16:19]
	v_mfma_f32_16x16x32_bf16 v[4:7], v[182:185], v[246:249], v[4:7]
	v_mfma_f32_16x16x32_bf16 v[0:3], v[200:203], v[246:249], v[0:3]
	s_setprio 0
	s_barrier
	s_add_i32 s27, 0, 0x18000
	v_add_u32_e32 v160, s27, v196
	s_add_i32 s85, 0, 0x1c000
	ds_read_b128 v[150:153], v160
	ds_read_b128 v[154:157], v160 offset:1024
	ds_read_b128 v[170:173], v160 offset:2048
	ds_read_b128 v[174:177], v160 offset:3072
	v_add_u32_e32 v160, s85, v196
	ds_read_b128 v[178:181], v160
	ds_read_b128 v[182:185], v160 offset:1024
	ds_read_b128 v[186:189], v160 offset:2048
	ds_read_b128 v[200:203], v160 offset:3072
	s_add_u32 s42, s42, 0x40000
	s_addc_u32 s43, s43, 0
	s_mov_b32 m0, s88
	ds_read_b128 v[204:207], v199 offset:32768
	ds_read_b128 v[208:211], v199 offset:33792
	ds_read_b128 v[212:215], v199 offset:34816
	ds_read_b128 v[222:225], v199 offset:35840
	ds_read_b128 v[234:237], v199 offset:36864
	ds_read_b128 v[238:241], v199 offset:37888
	ds_read_b128 v[242:245], v199 offset:38912
	ds_read_b128 v[246:249], v199 offset:39936
	global_load_lds_dwordx4 v128, s[42:43]
	s_mov_b32 m0, s89
	s_nop 0
	global_load_lds_dwordx4 v132, s[42:43]
	s_waitcnt vmcnt(8)
	s_waitcnt lgkmcnt(0)
	s_barrier
	s_setprio 1
	s_waitcnt lgkmcnt(0)
	v_mfma_f32_16x16x32_bf16 v[124:127], v[150:153], v[204:207], v[124:127]
	v_mfma_f32_16x16x32_bf16 v[120:123], v[170:173], v[204:207], v[120:123]
	v_mfma_f32_16x16x32_bf16 v[108:111], v[150:153], v[212:215], v[108:111]
	v_mfma_f32_16x16x32_bf16 v[104:107], v[170:173], v[212:215], v[104:107]
	v_mfma_f32_16x16x32_bf16 v[92:95], v[150:153], v[234:237], v[92:95]
	v_mfma_f32_16x16x32_bf16 v[88:91], v[170:173], v[234:237], v[88:91]
	v_mfma_f32_16x16x32_bf16 v[76:79], v[150:153], v[242:245], v[76:79]
	v_mfma_f32_16x16x32_bf16 v[72:75], v[170:173], v[242:245], v[72:75]
	v_mfma_f32_16x16x32_bf16 v[124:127], v[154:157], v[208:211], v[124:127]
	v_mfma_f32_16x16x32_bf16 v[120:123], v[174:177], v[208:211], v[120:123]
	v_mfma_f32_16x16x32_bf16 v[108:111], v[154:157], v[222:225], v[108:111]
	v_mfma_f32_16x16x32_bf16 v[104:107], v[174:177], v[222:225], v[104:107]
	v_mfma_f32_16x16x32_bf16 v[92:95], v[154:157], v[238:241], v[92:95]
	v_mfma_f32_16x16x32_bf16 v[88:91], v[174:177], v[238:241], v[88:91]
	v_mfma_f32_16x16x32_bf16 v[76:79], v[154:157], v[246:249], v[76:79]
	v_mfma_f32_16x16x32_bf16 v[72:75], v[174:177], v[246:249], v[72:75]
	v_mfma_f32_16x16x32_bf16 v[116:119], v[178:181], v[204:207], v[116:119]
	v_mfma_f32_16x16x32_bf16 v[112:115], v[186:189], v[204:207], v[112:115]
	v_mfma_f32_16x16x32_bf16 v[100:103], v[178:181], v[212:215], v[100:103]
	v_mfma_f32_16x16x32_bf16 v[96:99], v[186:189], v[212:215], v[96:99]
	v_mfma_f32_16x16x32_bf16 v[84:87], v[178:181], v[234:237], v[84:87]
	v_mfma_f32_16x16x32_bf16 v[80:83], v[186:189], v[234:237], v[80:83]
	v_mfma_f32_16x16x32_bf16 v[68:71], v[178:181], v[242:245], v[68:71]
	v_mfma_f32_16x16x32_bf16 v[64:67], v[186:189], v[242:245], v[64:67]
	v_mfma_f32_16x16x32_bf16 v[116:119], v[182:185], v[208:211], v[116:119]
	v_mfma_f32_16x16x32_bf16 v[112:115], v[200:203], v[208:211], v[112:115]
	v_mfma_f32_16x16x32_bf16 v[100:103], v[182:185], v[222:225], v[100:103]
	v_mfma_f32_16x16x32_bf16 v[96:99], v[200:203], v[222:225], v[96:99]
	v_mfma_f32_16x16x32_bf16 v[84:87], v[182:185], v[238:241], v[84:87]
	v_mfma_f32_16x16x32_bf16 v[80:83], v[200:203], v[238:241], v[80:83]
	v_mfma_f32_16x16x32_bf16 v[68:71], v[182:185], v[246:249], v[68:71]
	v_mfma_f32_16x16x32_bf16 v[64:67], v[200:203], v[246:249], v[64:67]
	s_setprio 0
	s_barrier
	s_add_i32 s27, s27, s86
	s_add_u32 s100, s12, 0x80
	s_addc_u32 s101, s13, 0
	s_mov_b32 m0, s27
	ds_read_b128 v[204:207], v199 offset:49152
	ds_read_b128 v[208:211], v199 offset:50176
	ds_read_b128 v[212:215], v199 offset:51200
	ds_read_b128 v[222:225], v199 offset:52224
	ds_read_b128 v[234:237], v199 offset:53248
	ds_read_b128 v[238:241], v199 offset:54272
	ds_read_b128 v[242:245], v199 offset:55296
	ds_read_b128 v[246:249], v199 offset:56320
	global_load_lds_dwordx4 v130, s[100:101]
	s_add_i32 m0, s27, 0x2000
	s_add_u32 s12, s12, 0x40080
	s_addc_u32 s13, s13, 0
	s_add_i32 s27, s85, s86
	global_load_lds_dwordx4 v134, s[100:101]
	s_mov_b32 m0, s27
	s_nop 0
	global_load_lds_dwordx4 v130, s[12:13]
	s_add_i32 m0, s27, 0x2000
	s_nop 0
	global_load_lds_dwordx4 v134, s[12:13]
	s_add_u32 s98, s42, 0xfffc0080
	s_addc_u32 s99, s43, -1
	s_mov_b32 m0, s92
	s_nop 0
	global_load_lds_dwordx4 v128, s[98:99]
	s_mov_b32 m0, s93
	s_nop 0
	global_load_lds_dwordx4 v132, s[98:99]
	s_waitcnt vmcnt(8)
	s_waitcnt lgkmcnt(0)
	s_barrier
	s_setprio 1
	s_waitcnt lgkmcnt(0)
	v_mfma_f32_16x16x32_bf16 v[60:63], v[150:153], v[204:207], v[60:63]
	v_mfma_f32_16x16x32_bf16 v[56:59], v[170:173], v[204:207], v[56:59]
	v_mfma_f32_16x16x32_bf16 v[44:47], v[150:153], v[212:215], v[44:47]
	v_mfma_f32_16x16x32_bf16 v[40:43], v[170:173], v[212:215], v[40:43]
	v_mfma_f32_16x16x32_bf16 v[28:31], v[150:153], v[234:237], v[28:31]
	v_mfma_f32_16x16x32_bf16 v[24:27], v[170:173], v[234:237], v[24:27]
	v_mfma_f32_16x16x32_bf16 v[12:15], v[150:153], v[242:245], v[12:15]
	v_mfma_f32_16x16x32_bf16 v[8:11], v[170:173], v[242:245], v[8:11]
	v_mfma_f32_16x16x32_bf16 v[60:63], v[154:157], v[208:211], v[60:63]
	v_mfma_f32_16x16x32_bf16 v[56:59], v[174:177], v[208:211], v[56:59]
	v_mfma_f32_16x16x32_bf16 v[44:47], v[154:157], v[222:225], v[44:47]
	v_mfma_f32_16x16x32_bf16 v[40:43], v[174:177], v[222:225], v[40:43]
	v_mfma_f32_16x16x32_bf16 v[28:31], v[154:157], v[238:241], v[28:31]
	v_mfma_f32_16x16x32_bf16 v[24:27], v[174:177], v[238:241], v[24:27]
	v_mfma_f32_16x16x32_bf16 v[12:15], v[154:157], v[246:249], v[12:15]
	v_mfma_f32_16x16x32_bf16 v[8:11], v[174:177], v[246:249], v[8:11]
	v_mfma_f32_16x16x32_bf16 v[52:55], v[178:181], v[204:207], v[52:55]
	v_mfma_f32_16x16x32_bf16 v[48:51], v[186:189], v[204:207], v[48:51]
	v_mfma_f32_16x16x32_bf16 v[36:39], v[178:181], v[212:215], v[36:39]
	v_mfma_f32_16x16x32_bf16 v[32:35], v[186:189], v[212:215], v[32:35]
	v_mfma_f32_16x16x32_bf16 v[20:23], v[178:181], v[234:237], v[20:23]
	v_mfma_f32_16x16x32_bf16 v[16:19], v[186:189], v[234:237], v[16:19]
	v_mfma_f32_16x16x32_bf16 v[4:7], v[178:181], v[242:245], v[4:7]
	v_mfma_f32_16x16x32_bf16 v[0:3], v[186:189], v[242:245], v[0:3]
	v_mfma_f32_16x16x32_bf16 v[52:55], v[182:185], v[208:211], v[52:55]
	v_mfma_f32_16x16x32_bf16 v[48:51], v[200:203], v[208:211], v[48:51]
	v_mfma_f32_16x16x32_bf16 v[36:39], v[182:185], v[222:225], v[36:39]
	v_mfma_f32_16x16x32_bf16 v[32:35], v[200:203], v[222:225], v[32:35]
	v_mfma_f32_16x16x32_bf16 v[20:23], v[182:185], v[238:241], v[20:23]
	v_mfma_f32_16x16x32_bf16 v[16:19], v[200:203], v[238:241], v[16:19]
	v_mfma_f32_16x16x32_bf16 v[4:7], v[182:185], v[246:249], v[4:7]
	v_mfma_f32_16x16x32_bf16 v[0:3], v[200:203], v[246:249], v[0:3]
	s_setprio 0
	s_barrier
	s_add_i32 s51, s51, 2
	s_add_u32 s40, s40, 0x100
	s_addc_u32 s41, s41, 0
	s_add_u32 s25, s25, 0x100
	s_addc_u32 s50, s50, 0
	s_cmp_gt_u32 s51, 13
.LBB0_478:
	s_add_u32 s12, s40, 0xfffc0080
	s_addc_u32 s13, s41, -1
	s_add_i32 s85, 0, 0x10000
	s_cmp_eq_u32 s51, 12
	s_cselect_b32 s43, s4, s13
	s_cselect_b32 s42, s9, s12
	v_add_u32_e32 v158, s85, v196
	s_cselect_b32 s13, s17, s50
	s_cselect_b32 s12, s24, s25
	s_add_i32 s27, 0, 0x14000
	ds_read_b128 v[150:153], v158
	ds_read_b128 v[154:157], v158 offset:1024
	ds_read_b128 v[170:173], v158 offset:2048
	ds_read_b128 v[174:177], v158 offset:3072
	v_add_u32_e32 v158, s27, v196
	ds_read_b128 v[178:181], v158
	ds_read_b128 v[182:185], v158 offset:1024
	ds_read_b128 v[186:189], v158 offset:2048
	ds_read_b128 v[200:203], v158 offset:3072
	s_add_i32 m0, s15, 0xc000
	ds_read_b128 v[204:207], v199
	ds_read_b128 v[208:211], v199 offset:1024
	ds_read_b128 v[212:215], v199 offset:2048
	ds_read_b128 v[234:237], v199 offset:3072
	ds_read_b128 v[238:241], v199 offset:4096
	ds_read_b128 v[242:245], v199 offset:5120
	ds_read_b128 v[246:249], v199 offset:6144
	ds_read_b128 v[222:225], v199 offset:7168
	global_load_lds_dwordx4 v146, s[40:41]
	s_add_i32 m0, s15, 0xe000
	s_nop 0
	global_load_lds_dwordx4 v148, s[40:41]
	s_waitcnt vmcnt(8)
	s_waitcnt lgkmcnt(0)
	s_barrier
	s_setprio 1
	s_waitcnt lgkmcnt(0)
	v_mfma_f32_16x16x32_bf16 v[124:127], v[150:153], v[204:207], v[124:127]
	v_mfma_f32_16x16x32_bf16 v[120:123], v[170:173], v[204:207], v[120:123]
	v_mfma_f32_16x16x32_bf16 v[108:111], v[150:153], v[212:215], v[108:111]
	v_mfma_f32_16x16x32_bf16 v[104:107], v[170:173], v[212:215], v[104:107]
	v_mfma_f32_16x16x32_bf16 v[92:95], v[150:153], v[238:241], v[92:95]
	v_mfma_f32_16x16x32_bf16 v[88:91], v[170:173], v[238:241], v[88:91]
	v_mfma_f32_16x16x32_bf16 v[76:79], v[150:153], v[246:249], v[76:79]
	v_mfma_f32_16x16x32_bf16 v[72:75], v[170:173], v[246:249], v[72:75]
	v_mfma_f32_16x16x32_bf16 v[124:127], v[154:157], v[208:211], v[124:127]
	v_mfma_f32_16x16x32_bf16 v[120:123], v[174:177], v[208:211], v[120:123]
	v_mfma_f32_16x16x32_bf16 v[108:111], v[154:157], v[234:237], v[108:111]
	v_mfma_f32_16x16x32_bf16 v[104:107], v[174:177], v[234:237], v[104:107]
	v_mfma_f32_16x16x32_bf16 v[92:95], v[154:157], v[242:245], v[92:95]
	v_mfma_f32_16x16x32_bf16 v[88:91], v[174:177], v[242:245], v[88:91]
	v_mfma_f32_16x16x32_bf16 v[76:79], v[154:157], v[222:225], v[76:79]
	v_mfma_f32_16x16x32_bf16 v[72:75], v[174:177], v[222:225], v[72:75]
	v_mfma_f32_16x16x32_bf16 v[116:119], v[178:181], v[204:207], v[116:119]
	v_mfma_f32_16x16x32_bf16 v[112:115], v[186:189], v[204:207], v[112:115]
	v_mfma_f32_16x16x32_bf16 v[100:103], v[178:181], v[212:215], v[100:103]
	v_mfma_f32_16x16x32_bf16 v[96:99], v[186:189], v[212:215], v[96:99]
	v_mfma_f32_16x16x32_bf16 v[84:87], v[178:181], v[238:241], v[84:87]
	v_mfma_f32_16x16x32_bf16 v[80:83], v[186:189], v[238:241], v[80:83]
	v_mfma_f32_16x16x32_bf16 v[68:71], v[178:181], v[246:249], v[68:71]
	v_mfma_f32_16x16x32_bf16 v[64:67], v[186:189], v[246:249], v[64:67]
	v_mfma_f32_16x16x32_bf16 v[116:119], v[182:185], v[208:211], v[116:119]
	v_mfma_f32_16x16x32_bf16 v[112:115], v[200:203], v[208:211], v[112:115]
	v_mfma_f32_16x16x32_bf16 v[100:103], v[182:185], v[234:237], v[100:103]
	v_mfma_f32_16x16x32_bf16 v[96:99], v[200:203], v[234:237], v[96:99]
	v_mfma_f32_16x16x32_bf16 v[84:87], v[182:185], v[242:245], v[84:87]
	v_mfma_f32_16x16x32_bf16 v[80:83], v[200:203], v[242:245], v[80:83]
	v_mfma_f32_16x16x32_bf16 v[68:71], v[182:185], v[222:225], v[68:71]
	v_mfma_f32_16x16x32_bf16 v[64:67], v[200:203], v[222:225], v[64:67]
	s_setprio 0
	s_barrier
	s_add_i32 s85, s85, s86
	s_mov_b32 m0, s85
	ds_read_b128 v[204:207], v199 offset:16384
	ds_read_b128 v[208:211], v199 offset:17408
	ds_read_b128 v[212:215], v199 offset:18432
	ds_read_b128 v[222:225], v199 offset:19456
	ds_read_b128 v[234:237], v199 offset:20480
	ds_read_b128 v[238:241], v199 offset:21504
	ds_read_b128 v[242:245], v199 offset:22528
	ds_read_b128 v[246:249], v199 offset:23552
	global_load_lds_dwordx4 v130, s[12:13]
	s_add_i32 m0, s85, 0x2000
	s_add_u32 s98, s12, 0x40000
	s_addc_u32 s99, s13, 0
	s_add_i32 s27, s27, s86
	global_load_lds_dwordx4 v134, s[12:13]
	s_mov_b32 m0, s27
	s_nop 0
	global_load_lds_dwordx4 v130, s[98:99]
	s_add_i32 m0, s27, 0x2000
	s_nop 0
	global_load_lds_dwordx4 v134, s[98:99]
	s_mov_b32 m0, s15
	s_nop 0
	global_load_lds_dwordx4 v128, s[42:43]
	s_mov_b32 m0, s87
	s_nop 0
	global_load_lds_dwordx4 v132, s[42:43]
	s_waitcnt vmcnt(8)
	s_waitcnt lgkmcnt(0)
	s_barrier
	s_setprio 1
	s_waitcnt lgkmcnt(0)
	v_mfma_f32_16x16x32_bf16 v[60:63], v[150:153], v[204:207], v[60:63]
	v_mfma_f32_16x16x32_bf16 v[56:59], v[170:173], v[204:207], v[56:59]
	v_mfma_f32_16x16x32_bf16 v[44:47], v[150:153], v[212:215], v[44:47]
	v_mfma_f32_16x16x32_bf16 v[40:43], v[170:173], v[212:215], v[40:43]
	v_mfma_f32_16x16x32_bf16 v[28:31], v[150:153], v[234:237], v[28:31]
	v_mfma_f32_16x16x32_bf16 v[24:27], v[170:173], v[234:237], v[24:27]
	v_mfma_f32_16x16x32_bf16 v[12:15], v[150:153], v[242:245], v[12:15]
	v_mfma_f32_16x16x32_bf16 v[8:11], v[170:173], v[242:245], v[8:11]
	v_mfma_f32_16x16x32_bf16 v[60:63], v[154:157], v[208:211], v[60:63]
	v_mfma_f32_16x16x32_bf16 v[56:59], v[174:177], v[208:211], v[56:59]
	v_mfma_f32_16x16x32_bf16 v[44:47], v[154:157], v[222:225], v[44:47]
	v_mfma_f32_16x16x32_bf16 v[40:43], v[174:177], v[222:225], v[40:43]
	v_mfma_f32_16x16x32_bf16 v[28:31], v[154:157], v[238:241], v[28:31]
	v_mfma_f32_16x16x32_bf16 v[24:27], v[174:177], v[238:241], v[24:27]
	v_mfma_f32_16x16x32_bf16 v[12:15], v[154:157], v[246:249], v[12:15]
	v_mfma_f32_16x16x32_bf16 v[8:11], v[174:177], v[246:249], v[8:11]
	v_mfma_f32_16x16x32_bf16 v[52:55], v[178:181], v[204:207], v[52:55]
	v_mfma_f32_16x16x32_bf16 v[48:51], v[186:189], v[204:207], v[48:51]
	v_mfma_f32_16x16x32_bf16 v[36:39], v[178:181], v[212:215], v[36:39]
	v_mfma_f32_16x16x32_bf16 v[32:35], v[186:189], v[212:215], v[32:35]
	v_mfma_f32_16x16x32_bf16 v[20:23], v[178:181], v[234:237], v[20:23]
	v_mfma_f32_16x16x32_bf16 v[16:19], v[186:189], v[234:237], v[16:19]
	v_mfma_f32_16x16x32_bf16 v[4:7], v[178:181], v[242:245], v[4:7]
	v_mfma_f32_16x16x32_bf16 v[0:3], v[186:189], v[242:245], v[0:3]
	v_mfma_f32_16x16x32_bf16 v[52:55], v[182:185], v[208:211], v[52:55]
	v_mfma_f32_16x16x32_bf16 v[48:51], v[200:203], v[208:211], v[48:51]
	v_mfma_f32_16x16x32_bf16 v[36:39], v[182:185], v[222:225], v[36:39]
	v_mfma_f32_16x16x32_bf16 v[32:35], v[200:203], v[222:225], v[32:35]
	v_mfma_f32_16x16x32_bf16 v[20:23], v[182:185], v[238:241], v[20:23]
	v_mfma_f32_16x16x32_bf16 v[16:19], v[200:203], v[238:241], v[16:19]
	v_mfma_f32_16x16x32_bf16 v[4:7], v[182:185], v[246:249], v[4:7]
	v_mfma_f32_16x16x32_bf16 v[0:3], v[200:203], v[246:249], v[0:3]
	s_setprio 0
	s_barrier
	s_add_i32 s27, 0, 0x18000
	v_add_u32_e32 v160, s27, v196
	s_add_i32 s85, 0, 0x1c000
	ds_read_b128 v[150:153], v160
	ds_read_b128 v[154:157], v160 offset:1024
	ds_read_b128 v[170:173], v160 offset:2048
	ds_read_b128 v[174:177], v160 offset:3072
	v_add_u32_e32 v160, s85, v196
	ds_read_b128 v[178:181], v160
	ds_read_b128 v[182:185], v160 offset:1024
	ds_read_b128 v[186:189], v160 offset:2048
	ds_read_b128 v[200:203], v160 offset:3072
	s_add_u32 s42, s42, 0x40000
	s_addc_u32 s43, s43, 0
	s_mov_b32 m0, s88
	ds_read_b128 v[204:207], v199 offset:32768
	ds_read_b128 v[208:211], v199 offset:33792
	ds_read_b128 v[212:215], v199 offset:34816
	ds_read_b128 v[222:225], v199 offset:35840
	ds_read_b128 v[234:237], v199 offset:36864
	ds_read_b128 v[238:241], v199 offset:37888
	ds_read_b128 v[242:245], v199 offset:38912
	ds_read_b128 v[246:249], v199 offset:39936
	global_load_lds_dwordx4 v128, s[42:43]
	s_mov_b32 m0, s89
	s_nop 0
	global_load_lds_dwordx4 v132, s[42:43]
	s_waitcnt vmcnt(8)
	s_waitcnt lgkmcnt(0)
	s_barrier
	s_setprio 1
	s_waitcnt lgkmcnt(0)
	v_mfma_f32_16x16x32_bf16 v[124:127], v[150:153], v[204:207], v[124:127]
	v_mfma_f32_16x16x32_bf16 v[120:123], v[170:173], v[204:207], v[120:123]
	v_mfma_f32_16x16x32_bf16 v[108:111], v[150:153], v[212:215], v[108:111]
	v_mfma_f32_16x16x32_bf16 v[104:107], v[170:173], v[212:215], v[104:107]
	v_mfma_f32_16x16x32_bf16 v[92:95], v[150:153], v[234:237], v[92:95]
	v_mfma_f32_16x16x32_bf16 v[88:91], v[170:173], v[234:237], v[88:91]
	v_mfma_f32_16x16x32_bf16 v[76:79], v[150:153], v[242:245], v[76:79]
	v_mfma_f32_16x16x32_bf16 v[72:75], v[170:173], v[242:245], v[72:75]
	v_mfma_f32_16x16x32_bf16 v[124:127], v[154:157], v[208:211], v[124:127]
	v_mfma_f32_16x16x32_bf16 v[120:123], v[174:177], v[208:211], v[120:123]
	v_mfma_f32_16x16x32_bf16 v[108:111], v[154:157], v[222:225], v[108:111]
	v_mfma_f32_16x16x32_bf16 v[104:107], v[174:177], v[222:225], v[104:107]
	v_mfma_f32_16x16x32_bf16 v[92:95], v[154:157], v[238:241], v[92:95]
	v_mfma_f32_16x16x32_bf16 v[88:91], v[174:177], v[238:241], v[88:91]
	v_mfma_f32_16x16x32_bf16 v[76:79], v[154:157], v[246:249], v[76:79]
	v_mfma_f32_16x16x32_bf16 v[72:75], v[174:177], v[246:249], v[72:75]
	v_mfma_f32_16x16x32_bf16 v[116:119], v[178:181], v[204:207], v[116:119]
	v_mfma_f32_16x16x32_bf16 v[112:115], v[186:189], v[204:207], v[112:115]
	v_mfma_f32_16x16x32_bf16 v[100:103], v[178:181], v[212:215], v[100:103]
	v_mfma_f32_16x16x32_bf16 v[96:99], v[186:189], v[212:215], v[96:99]
	v_mfma_f32_16x16x32_bf16 v[84:87], v[178:181], v[234:237], v[84:87]
	v_mfma_f32_16x16x32_bf16 v[80:83], v[186:189], v[234:237], v[80:83]
	v_mfma_f32_16x16x32_bf16 v[68:71], v[178:181], v[242:245], v[68:71]
	v_mfma_f32_16x16x32_bf16 v[64:67], v[186:189], v[242:245], v[64:67]
	v_mfma_f32_16x16x32_bf16 v[116:119], v[182:185], v[208:211], v[116:119]
	v_mfma_f32_16x16x32_bf16 v[112:115], v[200:203], v[208:211], v[112:115]
	v_mfma_f32_16x16x32_bf16 v[100:103], v[182:185], v[222:225], v[100:103]
	v_mfma_f32_16x16x32_bf16 v[96:99], v[200:203], v[222:225], v[96:99]
	v_mfma_f32_16x16x32_bf16 v[84:87], v[182:185], v[238:241], v[84:87]
	v_mfma_f32_16x16x32_bf16 v[80:83], v[200:203], v[238:241], v[80:83]
	v_mfma_f32_16x16x32_bf16 v[68:71], v[182:185], v[246:249], v[68:71]
	v_mfma_f32_16x16x32_bf16 v[64:67], v[200:203], v[246:249], v[64:67]
	s_setprio 0
	s_barrier
	s_add_i32 s27, s27, s86
	s_add_u32 s100, s12, 0x80
	s_addc_u32 s101, s13, 0
	s_mov_b32 m0, s27
	ds_read_b128 v[204:207], v199 offset:49152
	ds_read_b128 v[208:211], v199 offset:50176
	ds_read_b128 v[212:215], v199 offset:51200
	ds_read_b128 v[222:225], v199 offset:52224
	ds_read_b128 v[234:237], v199 offset:53248
	ds_read_b128 v[238:241], v199 offset:54272
	ds_read_b128 v[242:245], v199 offset:55296
	ds_read_b128 v[246:249], v199 offset:56320
	global_load_lds_dwordx4 v130, s[100:101]
	s_add_i32 m0, s27, 0x2000
	s_add_u32 s12, s12, 0x40080
	s_addc_u32 s13, s13, 0
	s_add_i32 s27, s85, s86
	global_load_lds_dwordx4 v134, s[100:101]
	s_mov_b32 m0, s27
	s_nop 0
	global_load_lds_dwordx4 v130, s[12:13]
	s_add_i32 m0, s27, 0x2000
	s_nop 0
	global_load_lds_dwordx4 v134, s[12:13]
	s_add_u32 s98, s42, 0xfffc0080
	s_addc_u32 s99, s43, -1
	s_mov_b32 m0, s92
	s_nop 0
	global_load_lds_dwordx4 v128, s[98:99]
	s_mov_b32 m0, s93
	s_nop 0
	global_load_lds_dwordx4 v132, s[98:99]
	s_waitcnt vmcnt(8)
	s_waitcnt lgkmcnt(0)
	s_barrier
	s_setprio 1
	s_waitcnt lgkmcnt(0)
	v_mfma_f32_16x16x32_bf16 v[60:63], v[150:153], v[204:207], v[60:63]
	v_mfma_f32_16x16x32_bf16 v[56:59], v[170:173], v[204:207], v[56:59]
	v_mfma_f32_16x16x32_bf16 v[44:47], v[150:153], v[212:215], v[44:47]
	v_mfma_f32_16x16x32_bf16 v[40:43], v[170:173], v[212:215], v[40:43]
	v_mfma_f32_16x16x32_bf16 v[28:31], v[150:153], v[234:237], v[28:31]
	v_mfma_f32_16x16x32_bf16 v[24:27], v[170:173], v[234:237], v[24:27]
	v_mfma_f32_16x16x32_bf16 v[12:15], v[150:153], v[242:245], v[12:15]
	v_mfma_f32_16x16x32_bf16 v[8:11], v[170:173], v[242:245], v[8:11]
	v_mfma_f32_16x16x32_bf16 v[60:63], v[154:157], v[208:211], v[60:63]
	v_mfma_f32_16x16x32_bf16 v[56:59], v[174:177], v[208:211], v[56:59]
	v_mfma_f32_16x16x32_bf16 v[44:47], v[154:157], v[222:225], v[44:47]
	v_mfma_f32_16x16x32_bf16 v[40:43], v[174:177], v[222:225], v[40:43]
	v_mfma_f32_16x16x32_bf16 v[28:31], v[154:157], v[238:241], v[28:31]
	v_mfma_f32_16x16x32_bf16 v[24:27], v[174:177], v[238:241], v[24:27]
	v_mfma_f32_16x16x32_bf16 v[12:15], v[154:157], v[246:249], v[12:15]
	v_mfma_f32_16x16x32_bf16 v[8:11], v[174:177], v[246:249], v[8:11]
	v_mfma_f32_16x16x32_bf16 v[52:55], v[178:181], v[204:207], v[52:55]
	v_mfma_f32_16x16x32_bf16 v[48:51], v[186:189], v[204:207], v[48:51]
	v_mfma_f32_16x16x32_bf16 v[36:39], v[178:181], v[212:215], v[36:39]
	v_mfma_f32_16x16x32_bf16 v[32:35], v[186:189], v[212:215], v[32:35]
	v_mfma_f32_16x16x32_bf16 v[20:23], v[178:181], v[234:237], v[20:23]
	v_mfma_f32_16x16x32_bf16 v[16:19], v[186:189], v[234:237], v[16:19]
	v_mfma_f32_16x16x32_bf16 v[4:7], v[178:181], v[242:245], v[4:7]
	v_mfma_f32_16x16x32_bf16 v[0:3], v[186:189], v[242:245], v[0:3]
	v_mfma_f32_16x16x32_bf16 v[52:55], v[182:185], v[208:211], v[52:55]
	v_mfma_f32_16x16x32_bf16 v[48:51], v[200:203], v[208:211], v[48:51]
	v_mfma_f32_16x16x32_bf16 v[36:39], v[182:185], v[222:225], v[36:39]
	v_mfma_f32_16x16x32_bf16 v[32:35], v[200:203], v[222:225], v[32:35]
	v_mfma_f32_16x16x32_bf16 v[20:23], v[182:185], v[238:241], v[20:23]
	v_mfma_f32_16x16x32_bf16 v[16:19], v[200:203], v[238:241], v[16:19]
	v_mfma_f32_16x16x32_bf16 v[4:7], v[182:185], v[246:249], v[4:7]
	v_mfma_f32_16x16x32_bf16 v[0:3], v[200:203], v[246:249], v[0:3]
	s_setprio 0
	s_barrier
	s_add_i32 s51, s51, 2
	s_add_u32 s40, s40, 0x100
	s_addc_u32 s41, s41, 0
	s_add_u32 s25, s25, 0x100
	s_addc_u32 s50, s50, 0
	s_cmp_gt_u32 s51, 13
	s_cbranch_scc0 .LBB0_478
	s_and_b64 vcc, exec, s[10:11]
	s_cbranch_vccz .LBB0_481
	s_barrier
